# combo18 + Swiglu epilogue: rstd-independent lane-index math and gate*up products moved above the pre-epilogue workgroup barrier
# baseline (speedup 1.0000x reference)
.LBB0_290:
	s_add_u32 s26, s24, 0xfffc0080
	s_addc_u32 s27, s25, -1
	s_add_u32 s52, s24, 0xfffc0000
	s_addc_u32 s53, s25, -1
	s_mov_b32 m0, s43
	ds_read_b128 v[130:133], v188
	ds_read_b128 v[134:137], v188 offset:1024
	ds_read_b128 v[138:141], v188 offset:2048
	ds_read_b128 v[154:157], v188 offset:3072
	ds_read_b128 v[158:161], v188 offset:16384
	ds_read_b128 v[162:165], v188 offset:17408
	ds_read_b128 v[166:169], v188 offset:18432
	ds_read_b128 v[176:179], v188 offset:19456
	ds_read_b128 v[180:183], v175
	ds_read_b128 v[184:187], v175 offset:1024
	ds_read_b128 v[192:195], v175 offset:2048
	ds_read_b128 v[196:199], v175 offset:3072
	ds_read_b128 v[200:203], v175 offset:4096
	ds_read_b128 v[204:207], v175 offset:5120
	ds_read_b128 v[208:211], v175 offset:6144
	ds_read_b128 v[212:215], v175 offset:7168
	global_load_lds_dwordx4 v144, s[52:53]
	s_add_i32 m0, s38, 0xc000
	s_nop 0
	global_load_lds_dwordx4 v150, s[24:25]
	s_add_i32 m0, s38, 0xe000
	s_cmp_eq_u32 s50, 12
	global_load_lds_dwordx4 v152, s[24:25]
	s_cselect_b32 s29, s17, s27
	s_cselect_b32 s28, s46, s26
	s_cselect_b32 s27, s15, s49
	s_cselect_b32 s26, s47, s48
	s_waitcnt vmcnt(8)
	s_waitcnt lgkmcnt(0)
	s_barrier
	s_setprio 1
	s_waitcnt lgkmcnt(0)
	v_mfma_f32_16x16x32_bf16 v[126:129], v[130:133], v[180:183], v[126:129]
	v_mfma_f32_16x16x32_bf16 v[122:125], v[138:141], v[180:183], v[122:125]
	v_mfma_f32_16x16x32_bf16 v[110:113], v[130:133], v[192:195], v[110:113]
	v_mfma_f32_16x16x32_bf16 v[106:109], v[138:141], v[192:195], v[106:109]
	v_mfma_f32_16x16x32_bf16 v[94:97], v[130:133], v[200:203], v[94:97]
	v_mfma_f32_16x16x32_bf16 v[90:93], v[138:141], v[200:203], v[90:93]
	v_mfma_f32_16x16x32_bf16 v[78:81], v[130:133], v[208:211], v[78:81]
	v_mfma_f32_16x16x32_bf16 v[74:77], v[138:141], v[208:211], v[74:77]
	v_mfma_f32_16x16x32_bf16 v[126:129], v[134:137], v[184:187], v[126:129]
	v_mfma_f32_16x16x32_bf16 v[122:125], v[154:157], v[184:187], v[122:125]
	v_mfma_f32_16x16x32_bf16 v[110:113], v[134:137], v[196:199], v[110:113]
	v_mfma_f32_16x16x32_bf16 v[106:109], v[154:157], v[196:199], v[106:109]
	v_mfma_f32_16x16x32_bf16 v[94:97], v[134:137], v[204:207], v[94:97]
	v_mfma_f32_16x16x32_bf16 v[90:93], v[154:157], v[204:207], v[90:93]
	v_mfma_f32_16x16x32_bf16 v[78:81], v[134:137], v[212:215], v[78:81]
	v_mfma_f32_16x16x32_bf16 v[74:77], v[154:157], v[212:215], v[74:77]
	s_setprio 0
	s_setprio 1
	v_mfma_f32_16x16x32_bf16 v[118:121], v[158:161], v[180:183], v[118:121]
	v_mfma_f32_16x16x32_bf16 v[114:117], v[166:169], v[180:183], v[114:117]
	v_mfma_f32_16x16x32_bf16 v[102:105], v[158:161], v[192:195], v[102:105]
	v_mfma_f32_16x16x32_bf16 v[98:101], v[166:169], v[192:195], v[98:101]
	v_mfma_f32_16x16x32_bf16 v[86:89], v[158:161], v[200:203], v[86:89]
	v_mfma_f32_16x16x32_bf16 v[82:85], v[166:169], v[200:203], v[82:85]
	v_mfma_f32_16x16x32_bf16 v[70:73], v[158:161], v[208:211], v[70:73]
	v_mfma_f32_16x16x32_bf16 v[66:69], v[166:169], v[208:211], v[66:69]
	v_mfma_f32_16x16x32_bf16 v[118:121], v[162:165], v[184:187], v[118:121]
	v_mfma_f32_16x16x32_bf16 v[114:117], v[176:179], v[184:187], v[114:117]
	v_mfma_f32_16x16x32_bf16 v[102:105], v[162:165], v[196:199], v[102:105]
	v_mfma_f32_16x16x32_bf16 v[98:101], v[176:179], v[196:199], v[98:101]
	v_mfma_f32_16x16x32_bf16 v[86:89], v[162:165], v[204:207], v[86:89]
	v_mfma_f32_16x16x32_bf16 v[82:85], v[176:179], v[204:207], v[82:85]
	v_mfma_f32_16x16x32_bf16 v[70:73], v[162:165], v[212:215], v[70:73]
	v_mfma_f32_16x16x32_bf16 v[66:69], v[176:179], v[212:215], v[66:69]
	s_setprio 0
	s_barrier
	s_add_i32 s51, s36, 0x10000
	s_mov_b32 m0, s51
	ds_read_b128 v[180:183], v175 offset:16384
	ds_read_b128 v[184:187], v175 offset:17408
	ds_read_b128 v[192:195], v175 offset:18432
	ds_read_b128 v[196:199], v175 offset:19456
	ds_read_b128 v[200:203], v175 offset:20480
	ds_read_b128 v[204:207], v175 offset:21504
	ds_read_b128 v[208:211], v175 offset:22528
	ds_read_b128 v[212:215], v175 offset:23552
	global_load_lds_dwordx4 v0, s[26:27]
	s_add_i32 m0, s51, 0x2000
	s_add_u32 s52, s26, 0x40000
	global_load_lds_dwordx4 v142, s[26:27]
	s_addc_u32 s53, s27, 0
	s_add_i32 s51, s36, 0x14000
	s_mov_b32 m0, s51
	s_nop 0
	global_load_lds_dwordx4 v0, s[52:53]
	s_add_i32 m0, s51, 0x2000
	s_nop 0
	global_load_lds_dwordx4 v142, s[52:53]
	s_mov_b32 m0, s38
	s_nop 0
	global_load_lds_dwordx4 v146, s[28:29]
	s_waitcnt vmcnt(7)
	s_waitcnt lgkmcnt(0)
	s_barrier
	s_setprio 1
	s_waitcnt lgkmcnt(0)
	v_mfma_f32_16x16x32_bf16 v[62:65], v[130:133], v[180:183], v[62:65]
	v_mfma_f32_16x16x32_bf16 v[58:61], v[138:141], v[180:183], v[58:61]
	v_mfma_f32_16x16x32_bf16 v[46:49], v[130:133], v[192:195], v[46:49]
	v_mfma_f32_16x16x32_bf16 v[42:45], v[138:141], v[192:195], v[42:45]
	v_mfma_f32_16x16x32_bf16 v[30:33], v[130:133], v[200:203], v[30:33]
	v_mfma_f32_16x16x32_bf16 v[26:29], v[138:141], v[200:203], v[26:29]
	v_mfma_f32_16x16x32_bf16 v[14:17], v[130:133], v[208:211], v[14:17]
	v_mfma_f32_16x16x32_bf16 v[10:13], v[138:141], v[208:211], v[10:13]
	v_mfma_f32_16x16x32_bf16 v[62:65], v[134:137], v[184:187], v[62:65]
	v_mfma_f32_16x16x32_bf16 v[58:61], v[154:157], v[184:187], v[58:61]
	v_mfma_f32_16x16x32_bf16 v[46:49], v[134:137], v[196:199], v[46:49]
	v_mfma_f32_16x16x32_bf16 v[42:45], v[154:157], v[196:199], v[42:45]
	v_mfma_f32_16x16x32_bf16 v[30:33], v[134:137], v[204:207], v[30:33]
	v_mfma_f32_16x16x32_bf16 v[26:29], v[154:157], v[204:207], v[26:29]
	v_mfma_f32_16x16x32_bf16 v[14:17], v[134:137], v[212:215], v[14:17]
	v_mfma_f32_16x16x32_bf16 v[10:13], v[154:157], v[212:215], v[10:13]
	s_setprio 0
	s_setprio 1
	v_mfma_f32_16x16x32_bf16 v[54:57], v[158:161], v[180:183], v[54:57]
	v_mfma_f32_16x16x32_bf16 v[50:53], v[166:169], v[180:183], v[50:53]
	v_mfma_f32_16x16x32_bf16 v[38:41], v[158:161], v[192:195], v[38:41]
	v_mfma_f32_16x16x32_bf16 v[34:37], v[166:169], v[192:195], v[34:37]
	v_mfma_f32_16x16x32_bf16 v[22:25], v[158:161], v[200:203], v[22:25]
	v_mfma_f32_16x16x32_bf16 v[18:21], v[166:169], v[200:203], v[18:21]
	v_mfma_f32_16x16x32_bf16 v[6:9], v[158:161], v[208:211], v[6:9]
	v_mfma_f32_16x16x32_bf16 v[2:5], v[166:169], v[208:211], v[2:5]
	v_mfma_f32_16x16x32_bf16 v[54:57], v[162:165], v[184:187], v[54:57]
	v_mfma_f32_16x16x32_bf16 v[50:53], v[176:179], v[184:187], v[50:53]
	v_mfma_f32_16x16x32_bf16 v[38:41], v[162:165], v[196:199], v[38:41]
	v_mfma_f32_16x16x32_bf16 v[34:37], v[176:179], v[196:199], v[34:37]
	v_mfma_f32_16x16x32_bf16 v[22:25], v[162:165], v[204:207], v[22:25]
	v_mfma_f32_16x16x32_bf16 v[18:21], v[176:179], v[204:207], v[18:21]
	v_mfma_f32_16x16x32_bf16 v[6:9], v[162:165], v[212:215], v[6:9]
	v_mfma_f32_16x16x32_bf16 v[2:5], v[176:179], v[212:215], v[2:5]
	s_setprio 0
	s_barrier
	s_mov_b32 m0, s39
	ds_read_b128 v[130:133], v188 offset:32768
	ds_read_b128 v[134:137], v188 offset:33792
	ds_read_b128 v[138:141], v188 offset:34816
	ds_read_b128 v[154:157], v188 offset:35840
	ds_read_b128 v[158:161], v188 offset:49152
	ds_read_b128 v[162:165], v188 offset:50176
	ds_read_b128 v[166:169], v188 offset:51200
	ds_read_b128 v[176:179], v188 offset:52224
	ds_read_b128 v[180:183], v175 offset:32768
	ds_read_b128 v[184:187], v175 offset:33792
	ds_read_b128 v[192:195], v175 offset:34816
	ds_read_b128 v[196:199], v175 offset:35840
	ds_read_b128 v[200:203], v175 offset:36864
	ds_read_b128 v[204:207], v175 offset:37888
	ds_read_b128 v[208:211], v175 offset:38912
	ds_read_b128 v[212:215], v175 offset:39936
	global_load_lds_dwordx4 v144, s[28:29]
	s_add_u32 s28, s28, 0x40000
	s_addc_u32 s29, s29, 0
	s_mov_b32 m0, s40
	s_nop 0
	global_load_lds_dwordx4 v146, s[28:29]
	s_mov_b32 m0, s41
	s_nop 0
	global_load_lds_dwordx4 v144, s[28:29]
	s_waitcnt vmcnt(8)
	s_waitcnt lgkmcnt(0)
	s_barrier
	s_setprio 1
	s_waitcnt lgkmcnt(0)
	v_mfma_f32_16x16x32_bf16 v[126:129], v[130:133], v[180:183], v[126:129]
	v_mfma_f32_16x16x32_bf16 v[122:125], v[138:141], v[180:183], v[122:125]
	v_mfma_f32_16x16x32_bf16 v[110:113], v[130:133], v[192:195], v[110:113]
	v_mfma_f32_16x16x32_bf16 v[106:109], v[138:141], v[192:195], v[106:109]
	v_mfma_f32_16x16x32_bf16 v[94:97], v[130:133], v[200:203], v[94:97]
	v_mfma_f32_16x16x32_bf16 v[90:93], v[138:141], v[200:203], v[90:93]
	v_mfma_f32_16x16x32_bf16 v[78:81], v[130:133], v[208:211], v[78:81]
	v_mfma_f32_16x16x32_bf16 v[74:77], v[138:141], v[208:211], v[74:77]
	v_mfma_f32_16x16x32_bf16 v[126:129], v[134:137], v[184:187], v[126:129]
	v_mfma_f32_16x16x32_bf16 v[122:125], v[154:157], v[184:187], v[122:125]
	v_mfma_f32_16x16x32_bf16 v[110:113], v[134:137], v[196:199], v[110:113]
	v_mfma_f32_16x16x32_bf16 v[106:109], v[154:157], v[196:199], v[106:109]
	v_mfma_f32_16x16x32_bf16 v[94:97], v[134:137], v[204:207], v[94:97]
	v_mfma_f32_16x16x32_bf16 v[90:93], v[154:157], v[204:207], v[90:93]
	v_mfma_f32_16x16x32_bf16 v[78:81], v[134:137], v[212:215], v[78:81]
	v_mfma_f32_16x16x32_bf16 v[74:77], v[154:157], v[212:215], v[74:77]
	s_setprio 0
	s_setprio 1
	v_mfma_f32_16x16x32_bf16 v[118:121], v[158:161], v[180:183], v[118:121]
	v_mfma_f32_16x16x32_bf16 v[114:117], v[166:169], v[180:183], v[114:117]
	v_mfma_f32_16x16x32_bf16 v[102:105], v[158:161], v[192:195], v[102:105]
	v_mfma_f32_16x16x32_bf16 v[98:101], v[166:169], v[192:195], v[98:101]
	v_mfma_f32_16x16x32_bf16 v[86:89], v[158:161], v[200:203], v[86:89]
	v_mfma_f32_16x16x32_bf16 v[82:85], v[166:169], v[200:203], v[82:85]
	v_mfma_f32_16x16x32_bf16 v[70:73], v[158:161], v[208:211], v[70:73]
	v_mfma_f32_16x16x32_bf16 v[66:69], v[166:169], v[208:211], v[66:69]
	v_mfma_f32_16x16x32_bf16 v[118:121], v[162:165], v[184:187], v[118:121]
	v_mfma_f32_16x16x32_bf16 v[114:117], v[176:179], v[184:187], v[114:117]
	v_mfma_f32_16x16x32_bf16 v[102:105], v[162:165], v[196:199], v[102:105]
	v_mfma_f32_16x16x32_bf16 v[98:101], v[176:179], v[196:199], v[98:101]
	v_mfma_f32_16x16x32_bf16 v[86:89], v[162:165], v[204:207], v[86:89]
	v_mfma_f32_16x16x32_bf16 v[82:85], v[176:179], v[204:207], v[82:85]
	v_mfma_f32_16x16x32_bf16 v[70:73], v[162:165], v[212:215], v[70:73]
	v_mfma_f32_16x16x32_bf16 v[66:69], v[176:179], v[212:215], v[66:69]
	s_setprio 0
	s_barrier
	s_add_u32 s26, s26, 0x80
	s_addc_u32 s27, s27, 0
	s_add_i32 s51, s36, 0x18000
	s_mov_b32 m0, s51
	ds_read_b128 v[180:183], v175 offset:49152
	ds_read_b128 v[184:187], v175 offset:50176
	ds_read_b128 v[192:195], v175 offset:51200
	ds_read_b128 v[196:199], v175 offset:52224
	ds_read_b128 v[200:203], v175 offset:53248
	ds_read_b128 v[204:207], v175 offset:54272
	ds_read_b128 v[208:211], v175 offset:55296
	ds_read_b128 v[212:215], v175 offset:56320
	global_load_lds_dwordx4 v0, s[26:27]
	s_add_i32 m0, s51, 0x2000
	s_add_u32 s52, s26, 0x40000
	global_load_lds_dwordx4 v142, s[26:27]
	s_addc_u32 s53, s27, 0
	s_add_i32 s51, s36, 0x1c000
	s_mov_b32 m0, s51
	s_add_u32 s28, s28, 0xfffc0080
	global_load_lds_dwordx4 v0, s[52:53]
	s_addc_u32 s29, s29, -1
	s_add_i32 m0, s51, 0x2000
	s_nop 0
	global_load_lds_dwordx4 v142, s[52:53]
	s_mov_b32 m0, s42
	s_nop 0
	global_load_lds_dwordx4 v146, s[28:29]
	s_waitcnt vmcnt(7)
	s_waitcnt lgkmcnt(0)
	s_barrier
	s_setprio 1
	s_waitcnt lgkmcnt(0)
	v_mfma_f32_16x16x32_bf16 v[62:65], v[130:133], v[180:183], v[62:65]
	v_mfma_f32_16x16x32_bf16 v[58:61], v[138:141], v[180:183], v[58:61]
	v_mfma_f32_16x16x32_bf16 v[46:49], v[130:133], v[192:195], v[46:49]
	v_mfma_f32_16x16x32_bf16 v[42:45], v[138:141], v[192:195], v[42:45]
	v_mfma_f32_16x16x32_bf16 v[30:33], v[130:133], v[200:203], v[30:33]
	v_mfma_f32_16x16x32_bf16 v[26:29], v[138:141], v[200:203], v[26:29]
	v_mfma_f32_16x16x32_bf16 v[14:17], v[130:133], v[208:211], v[14:17]
	v_mfma_f32_16x16x32_bf16 v[10:13], v[138:141], v[208:211], v[10:13]
	v_mfma_f32_16x16x32_bf16 v[62:65], v[134:137], v[184:187], v[62:65]
	v_mfma_f32_16x16x32_bf16 v[58:61], v[154:157], v[184:187], v[58:61]
	v_mfma_f32_16x16x32_bf16 v[46:49], v[134:137], v[196:199], v[46:49]
	v_mfma_f32_16x16x32_bf16 v[42:45], v[154:157], v[196:199], v[42:45]
	v_mfma_f32_16x16x32_bf16 v[30:33], v[134:137], v[204:207], v[30:33]
	v_mfma_f32_16x16x32_bf16 v[26:29], v[154:157], v[204:207], v[26:29]
	v_mfma_f32_16x16x32_bf16 v[14:17], v[134:137], v[212:215], v[14:17]
	v_mfma_f32_16x16x32_bf16 v[10:13], v[154:157], v[212:215], v[10:13]
	s_setprio 0
	s_setprio 1
	v_mfma_f32_16x16x32_bf16 v[54:57], v[158:161], v[180:183], v[54:57]
	v_mfma_f32_16x16x32_bf16 v[50:53], v[166:169], v[180:183], v[50:53]
	v_mfma_f32_16x16x32_bf16 v[38:41], v[158:161], v[192:195], v[38:41]
	v_mfma_f32_16x16x32_bf16 v[34:37], v[166:169], v[192:195], v[34:37]
	v_mfma_f32_16x16x32_bf16 v[22:25], v[158:161], v[200:203], v[22:25]
	v_mfma_f32_16x16x32_bf16 v[18:21], v[166:169], v[200:203], v[18:21]
	v_mfma_f32_16x16x32_bf16 v[6:9], v[158:161], v[208:211], v[6:9]
	v_mfma_f32_16x16x32_bf16 v[2:5], v[166:169], v[208:211], v[2:5]
	v_mfma_f32_16x16x32_bf16 v[54:57], v[162:165], v[184:187], v[54:57]
	v_mfma_f32_16x16x32_bf16 v[50:53], v[176:179], v[184:187], v[50:53]
	v_mfma_f32_16x16x32_bf16 v[38:41], v[162:165], v[196:199], v[38:41]
	v_mfma_f32_16x16x32_bf16 v[34:37], v[176:179], v[196:199], v[34:37]
	v_mfma_f32_16x16x32_bf16 v[22:25], v[162:165], v[204:207], v[22:25]
	v_mfma_f32_16x16x32_bf16 v[18:21], v[176:179], v[204:207], v[18:21]
	v_mfma_f32_16x16x32_bf16 v[6:9], v[162:165], v[212:215], v[6:9]
	v_mfma_f32_16x16x32_bf16 v[2:5], v[176:179], v[212:215], v[2:5]
	s_setprio 0
	s_barrier
	s_add_i32 s50, s50, 2
	s_add_u32 s24, s24, 0x100
	s_addc_u32 s25, s25, 0
	s_add_u32 s48, s48, 0x100
	s_addc_u32 s49, s49, 0
	s_cmp_gt_u32 s50, 13
	s_cbranch_scc0 .LBB0_290
	v_lshl_add_u32 v168, s22, 8, v172
	v_ashrrev_i32_e32 v169, 31, v168
	v_lshlrev_b64 v[130:131], 6, v[168:169]
	v_lshl_add_u64 v[130:131], v[148:149], 0, v[130:131]
	global_load_dwordx4 v[176:179], v[130:131], off
	v_or_b32_e32 v166, 16, v168
	v_ashrrev_i32_e32 v167, 31, v166
	v_lshlrev_b64 v[130:131], 6, v[166:167]
	v_lshl_add_u64 v[130:131], v[148:149], 0, v[130:131]
	global_load_dwordx4 v[180:183], v[130:131], off
	v_or_b32_e32 v164, 32, v168
	v_ashrrev_i32_e32 v165, 31, v164
	v_lshlrev_b64 v[130:131], 6, v[164:165]
	v_lshl_add_u64 v[130:131], v[148:149], 0, v[130:131]
	global_load_dwordx4 v[184:187], v[130:131], off
	v_or_b32_e32 v162, 48, v168
	v_ashrrev_i32_e32 v163, 31, v162
	v_lshlrev_b64 v[130:131], 6, v[162:163]
	v_lshl_add_u64 v[130:131], v[148:149], 0, v[130:131]
	global_load_dwordx4 v[192:195], v[130:131], off
	v_add_u32_e32 v160, 0x80, v168
	v_ashrrev_i32_e32 v161, 31, v160
	v_lshlrev_b64 v[130:131], 6, v[160:161]
	v_add_u32_e32 v158, 0x90, v168
	v_lshl_add_u64 v[130:131], v[148:149], 0, v[130:131]
	v_ashrrev_i32_e32 v159, 31, v158
	global_load_dwordx4 v[196:199], v[130:131], off
	v_lshlrev_b64 v[130:131], 6, v[158:159]
	v_add_u32_e32 v156, 0xa0, v168
	v_lshl_add_u64 v[130:131], v[148:149], 0, v[130:131]
	v_ashrrev_i32_e32 v157, 31, v156
	global_load_dwordx4 v[138:141], v[130:131], off
	v_lshlrev_b64 v[130:131], 6, v[156:157]
	v_add_u32_e32 v154, 0xb0, v168
	v_lshl_add_u64 v[130:131], v[148:149], 0, v[130:131]
	v_ashrrev_i32_e32 v155, 31, v154
	global_load_dwordx4 v[134:137], v[130:131], off
	v_lshlrev_b64 v[130:131], 6, v[154:155]
	v_lshl_add_u64 v[130:131], v[148:149], 0, v[130:131]
	global_load_dwordx4 v[130:133], v[130:131], off
	v_cmp_lt_i32_e32 vcc, v239, v244
	v_lshl_or_b32 v170, s23, 7, v174
	v_ashrrev_i32_e32 v171, 31, v170
	v_cndmask_b32_e32 v155, v234, v239, vcc
	v_cmp_lt_i32_e32 vcc, v240, v244
	v_lshlrev_b32_e32 v163, 2, v155
	v_pk_mul_f32 v[116:117], v[124:125], v[116:117]
	v_cndmask_b32_e32 v155, v234, v240, vcc
	v_lshlrev_b32_e32 v165, 2, v155
	v_pk_mul_f32 v[114:115], v[122:123], v[114:115]
	v_pk_mul_f32 v[120:121], v[128:129], v[120:121]
	v_pk_mul_f32 v[118:119], v[126:127], v[118:119]
	v_pk_mul_f32 v[100:101], v[108:109], v[100:101]
	v_pk_mul_f32 v[98:99], v[106:107], v[98:99]
	v_pk_mul_f32 v[104:105], v[112:113], v[104:105]
	v_pk_mul_f32 v[102:103], v[110:111], v[102:103]
	v_pk_mul_f32 v[84:85], v[92:93], v[84:85]
	v_pk_mul_f32 v[82:83], v[90:91], v[82:83]
	v_pk_mul_f32 v[88:89], v[96:97], v[88:89]
	v_pk_mul_f32 v[86:87], v[94:95], v[86:87]
	v_pk_mul_f32 v[68:69], v[76:77], v[68:69]
	v_pk_mul_f32 v[66:67], v[74:75], v[66:67]
	v_pk_mul_f32 v[72:73], v[80:81], v[72:73]
	v_pk_mul_f32 v[70:71], v[78:79], v[70:71]
	v_pk_mul_f32 v[52:53], v[60:61], v[52:53]
	v_pk_mul_f32 v[50:51], v[58:59], v[50:51]
	v_pk_mul_f32 v[56:57], v[64:65], v[56:57]
	v_pk_mul_f32 v[54:55], v[62:63], v[54:55]
	v_pk_mul_f32 v[36:37], v[44:45], v[36:37]
	v_pk_mul_f32 v[34:35], v[42:43], v[34:35]
	v_pk_mul_f32 v[40:41], v[48:49], v[40:41]
	v_pk_mul_f32 v[38:39], v[46:47], v[38:39]
	v_pk_mul_f32 v[20:21], v[28:29], v[20:21]
	v_pk_mul_f32 v[18:19], v[26:27], v[18:19]
	v_pk_mul_f32 v[24:25], v[32:33], v[24:25]
	v_pk_mul_f32 v[22:23], v[30:31], v[22:23]
	v_pk_mul_f32 v[4:5], v[12:13], v[4:5]
	v_pk_mul_f32 v[2:3], v[10:11], v[2:3]
	v_pk_mul_f32 v[8:9], v[16:17], v[8:9]
	v_pk_mul_f32 v[6:7], v[14:15], v[6:7]
	s_and_b64 vcc, exec, s[12:13]
	s_cbranch_vccz .LBB0_293
	s_barrier
.LBB0_293:
	s_andn2_b64 vcc, exec, s[6:7]
	s_waitcnt vmcnt(0)
	v_add_f32_e32 v176, v176, v177
	v_add_f32_e32 v178, v178, v179
	v_add_f32_e32 v180, v180, v181
	v_add_f32_e32 v182, v182, v183
	v_add_f32_e32 v184, v184, v185
	v_add_f32_e32 v186, v186, v187
	v_add_f32_e32 v192, v192, v193
	v_add_f32_e32 v194, v194, v195
	v_add_f32_e32 v176, v176, v178
	v_add_f32_e32 v180, v180, v182
	v_add_f32_e32 v184, v184, v186
	v_add_f32_e32 v192, v192, v194
	ds_bpermute_b32 v177, v163, v176
	ds_bpermute_b32 v181, v163, v180
	ds_bpermute_b32 v185, v163, v184
	ds_bpermute_b32 v193, v163, v192
	s_waitcnt lgkmcnt(3)
	v_add_f32_e32 v176, v176, v177
	ds_bpermute_b32 v177, v165, v176
	s_waitcnt lgkmcnt(3)
	v_add_f32_e32 v180, v180, v181
	ds_bpermute_b32 v181, v165, v180
	s_waitcnt lgkmcnt(3)
	v_add_f32_e32 v184, v184, v185
	ds_bpermute_b32 v185, v165, v184
	s_waitcnt lgkmcnt(3)
	v_add_f32_e32 v192, v192, v193
	ds_bpermute_b32 v193, v165, v192
	s_waitcnt lgkmcnt(3)
	v_add_f32_e32 v176, v176, v177
	s_waitcnt lgkmcnt(2)
	v_add_f32_e32 v180, v180, v181
	s_waitcnt lgkmcnt(1)
	v_add_f32_e32 v184, v184, v185
	s_waitcnt lgkmcnt(0)
	v_add_f32_e32 v192, v192, v193
	v_fmamk_f32 v176, v176, 0x3a800000, v223
	v_fmamk_f32 v180, v180, 0x3a800000, v223
	v_fmamk_f32 v184, v184, 0x3a800000, v223
	v_fmamk_f32 v192, v192, 0x3a800000, v223
	v_rsq_f32_e32 v167, v176
	v_rsq_f32_e32 v161, v180
	v_rsq_f32_e32 v159, v184
	v_rsq_f32_e32 v157, v192
	v_mov_b32_e32 v176, v197
	v_mov_b32_e32 v177, v198
	v_mov_b32_e32 v197, v199
	v_pk_add_f32 v[176:177], v[176:177], v[196:197]
	s_nop 0
	v_add_f32_e32 v155, v176, v177
	v_mov_b32_e32 v176, v139
	v_mov_b32_e32 v177, v140
	v_mov_b32_e32 v139, v141
	v_mov_b32_e32 v140, v135
	v_mov_b32_e32 v141, v136
	v_mov_b32_e32 v135, v137
	v_mov_b32_e32 v136, v131
	v_mov_b32_e32 v137, v132
	v_mov_b32_e32 v131, v133
	v_pk_add_f32 v[134:135], v[140:141], v[134:135]
	v_pk_add_f32 v[130:131], v[136:137], v[130:131]
	v_add_f32_e32 v134, v134, v135
	v_add_f32_e32 v130, v130, v131
	ds_bpermute_b32 v135, v163, v134
	ds_bpermute_b32 v131, v163, v130
	ds_bpermute_b32 v169, v163, v155
	v_mul_f32_e32 v140, 0xbfb8aa3b, v167
	v_pk_add_f32 v[138:139], v[176:177], v[138:139]
	s_waitcnt lgkmcnt(2)
	v_add_f32_e32 v134, v134, v135
	s_waitcnt lgkmcnt(1)
	v_add_f32_e32 v130, v130, v131
	v_lshlrev_b64 v[132:133], 1, v[170:171]
	v_pk_mul_f32 v[170:171], v[128:129], v[140:141] op_sel_hi:[1,0]
	v_pk_mul_f32 v[176:177], v[126:127], v[140:141] op_sel_hi:[1,0]
	ds_bpermute_b32 v135, v165, v134
	ds_bpermute_b32 v131, v165, v130
	v_pk_mul_f32 v[178:179], v[124:125], v[140:141] op_sel_hi:[1,0]
	v_pk_mul_f32 v[140:141], v[122:123], v[140:141] op_sel_hi:[1,0]
	v_exp_f32_e32 v176, v176
	v_exp_f32_e32 v177, v177
	v_exp_f32_e32 v170, v170
	v_exp_f32_e32 v171, v171
	v_exp_f32_e32 v140, v140
	v_exp_f32_e32 v141, v141
	v_exp_f32_e32 v178, v178
	v_exp_f32_e32 v179, v179
	s_waitcnt lgkmcnt(2)
	v_add_f32_e32 v155, v155, v169
	ds_bpermute_b32 v169, v165, v155
	v_pk_add_f32 v[170:171], v[170:171], 1.0 op_sel_hi:[1,0]
	v_pk_add_f32 v[176:177], v[176:177], 1.0 op_sel_hi:[1,0]
	s_waitcnt lgkmcnt(2)
	v_add_f32_e32 v134, v134, v135
	s_waitcnt lgkmcnt(1)
	v_add_f32_e32 v130, v130, v131
	v_pk_add_f32 v[178:179], v[178:179], 1.0 op_sel_hi:[1,0]
	v_pk_add_f32 v[140:141], v[140:141], 1.0 op_sel_hi:[1,0]
	v_rcp_f32_e32 v122, v176
	v_rcp_f32_e32 v123, v177
	v_rcp_f32_e32 v124, v170
	v_rcp_f32_e32 v125, v171
	v_fmamk_f32 v134, v134, 0x3a800000, v223
	v_fmamk_f32 v130, v130, 0x3a800000, v223
	v_rcp_f32_e32 v126, v140
	v_rcp_f32_e32 v127, v141
	v_rcp_f32_e32 v128, v178
	v_rcp_f32_e32 v129, v179
	v_rsq_f32_e32 v135, v134
	v_rsq_f32_e32 v134, v130
	v_mov_b64_e32 v[130:131], s[10:11]
	v_mad_i64_i32 v[136:137], s[22:23], v168, s57, v[130:131]
	v_mul_f32_e32 v168, v167, v167
	s_waitcnt lgkmcnt(0)
	v_pk_mul_f32 v[122:123], v[168:169], v[122:123] op_sel_hi:[0,1]
	v_pk_mul_f32 v[124:125], v[168:169], v[124:125] op_sel_hi:[0,1]
	v_pk_mul_f32 v[120:121], v[120:121], v[124:125]
	v_pk_mul_f32 v[118:119], v[118:119], v[122:123]
	v_pk_mul_f32 v[122:123], v[168:169], v[126:127] op_sel_hi:[0,1]
	v_pk_mul_f32 v[124:125], v[168:169], v[128:129] op_sel_hi:[0,1]
	v_pk_mul_f32 v[124:125], v[116:117], v[124:125]
	v_pk_mul_f32 v[116:117], v[114:115], v[122:123]
	v_lshl_add_u64 v[136:137], v[136:137], 0, v[132:133]
	v_cvt_pk_bf16_f32 v114, v118, v119
	v_cvt_pk_bf16_f32 v115, v120, v121
	v_cvt_pk_bf16_f32 v116, v116, v117
	v_cvt_pk_bf16_f32 v117, v124, v125
	global_store_dwordx4 v[136:137], v[114:117], off
	v_mul_f32_e32 v118, v161, v161
	v_add_f32_e32 v155, v155, v169
	v_mul_f32_e32 v116, 0xbfb8aa3b, v161
	v_pk_mul_f32 v[120:121], v[112:113], v[116:117] op_sel_hi:[1,0]
	v_pk_mul_f32 v[122:123], v[110:111], v[116:117] op_sel_hi:[1,0]
	v_pk_mul_f32 v[124:125], v[108:109], v[116:117] op_sel_hi:[1,0]
	v_pk_mul_f32 v[116:117], v[106:107], v[116:117] op_sel_hi:[1,0]
	v_exp_f32_e32 v122, v122
	v_exp_f32_e32 v123, v123
	v_exp_f32_e32 v120, v120
	v_exp_f32_e32 v121, v121
	v_exp_f32_e32 v116, v116
	v_exp_f32_e32 v117, v117
	v_exp_f32_e32 v124, v124
	v_exp_f32_e32 v125, v125
	v_pk_add_f32 v[120:121], v[120:121], 1.0 op_sel_hi:[1,0]
	v_pk_add_f32 v[122:123], v[122:123], 1.0 op_sel_hi:[1,0]
	v_pk_add_f32 v[116:117], v[116:117], 1.0 op_sel_hi:[1,0]
	v_pk_add_f32 v[124:125], v[124:125], 1.0 op_sel_hi:[1,0]
	v_rcp_f32_e32 v106, v122
	v_rcp_f32_e32 v107, v123
	v_rcp_f32_e32 v108, v120
	v_rcp_f32_e32 v109, v121
	v_rcp_f32_e32 v110, v116
	v_rcp_f32_e32 v111, v117
	v_rcp_f32_e32 v112, v124
	v_rcp_f32_e32 v113, v125
	v_pk_mul_f32 v[106:107], v[118:119], v[106:107] op_sel_hi:[0,1]
	v_pk_mul_f32 v[108:109], v[118:119], v[108:109] op_sel_hi:[0,1]
	v_pk_mul_f32 v[104:105], v[104:105], v[108:109]
	v_pk_mul_f32 v[102:103], v[102:103], v[106:107]
	v_pk_mul_f32 v[106:107], v[118:119], v[110:111] op_sel_hi:[0,1]
	v_pk_mul_f32 v[108:109], v[118:119], v[112:113] op_sel_hi:[0,1]
	v_mad_i64_i32 v[114:115], s[22:23], v166, s57, v[130:131]
	v_pk_mul_f32 v[108:109], v[100:101], v[108:109]
	v_pk_mul_f32 v[100:101], v[98:99], v[106:107]
	v_lshl_add_u64 v[114:115], v[114:115], 0, v[132:133]
	v_cvt_pk_bf16_f32 v98, v102, v103
	v_cvt_pk_bf16_f32 v99, v104, v105
	v_cvt_pk_bf16_f32 v100, v100, v101
	v_cvt_pk_bf16_f32 v101, v108, v109
	global_store_dwordx4 v[114:115], v[98:101], off
	v_mul_f32_e32 v102, v159, v159
	v_fmamk_f32 v155, v155, 0x3a800000, v223
	v_mul_f32_e32 v100, 0xbfb8aa3b, v159
	v_pk_mul_f32 v[104:105], v[96:97], v[100:101] op_sel_hi:[1,0]
	v_pk_mul_f32 v[106:107], v[94:95], v[100:101] op_sel_hi:[1,0]
	v_pk_mul_f32 v[108:109], v[92:93], v[100:101] op_sel_hi:[1,0]
	v_pk_mul_f32 v[100:101], v[90:91], v[100:101] op_sel_hi:[1,0]
	v_exp_f32_e32 v106, v106
	v_exp_f32_e32 v107, v107
	v_exp_f32_e32 v104, v104
	v_exp_f32_e32 v105, v105
	v_exp_f32_e32 v100, v100
	v_exp_f32_e32 v101, v101
	v_exp_f32_e32 v108, v108
	v_exp_f32_e32 v109, v109
	v_pk_add_f32 v[104:105], v[104:105], 1.0 op_sel_hi:[1,0]
	v_pk_add_f32 v[106:107], v[106:107], 1.0 op_sel_hi:[1,0]
	v_pk_add_f32 v[100:101], v[100:101], 1.0 op_sel_hi:[1,0]
	v_pk_add_f32 v[108:109], v[108:109], 1.0 op_sel_hi:[1,0]
	v_rcp_f32_e32 v90, v106
	v_rcp_f32_e32 v91, v107
	v_rcp_f32_e32 v92, v104
	v_rcp_f32_e32 v93, v105
	v_rcp_f32_e32 v94, v100
	v_rcp_f32_e32 v95, v101
	v_rcp_f32_e32 v96, v108
	v_rcp_f32_e32 v97, v109
	v_pk_mul_f32 v[90:91], v[102:103], v[90:91] op_sel_hi:[0,1]
	v_pk_mul_f32 v[92:93], v[102:103], v[92:93] op_sel_hi:[0,1]
	v_pk_mul_f32 v[88:89], v[88:89], v[92:93]
	v_pk_mul_f32 v[86:87], v[86:87], v[90:91]
	v_pk_mul_f32 v[90:91], v[102:103], v[94:95] op_sel_hi:[0,1]
	v_pk_mul_f32 v[92:93], v[102:103], v[96:97] op_sel_hi:[0,1]
	v_mad_i64_i32 v[98:99], s[22:23], v164, s57, v[130:131]
	v_pk_mul_f32 v[92:93], v[84:85], v[92:93]
	v_pk_mul_f32 v[84:85], v[82:83], v[90:91]
	v_lshl_add_u64 v[98:99], v[98:99], 0, v[132:133]
	v_cvt_pk_bf16_f32 v82, v86, v87
	v_cvt_pk_bf16_f32 v83, v88, v89
	v_cvt_pk_bf16_f32 v84, v84, v85
	v_cvt_pk_bf16_f32 v85, v92, v93
	global_store_dwordx4 v[98:99], v[82:85], off
	v_mul_f32_e32 v86, v157, v157
	v_rsq_f32_e32 v155, v155
	v_mul_f32_e32 v84, 0xbfb8aa3b, v157
	v_pk_mul_f32 v[88:89], v[80:81], v[84:85] op_sel_hi:[1,0]
	v_pk_mul_f32 v[90:91], v[78:79], v[84:85] op_sel_hi:[1,0]
	v_pk_mul_f32 v[92:93], v[76:77], v[84:85] op_sel_hi:[1,0]
	v_pk_mul_f32 v[84:85], v[74:75], v[84:85] op_sel_hi:[1,0]
	v_exp_f32_e32 v90, v90
	v_exp_f32_e32 v91, v91
	v_exp_f32_e32 v88, v88
	v_exp_f32_e32 v89, v89
	v_exp_f32_e32 v84, v84
	v_exp_f32_e32 v85, v85
	v_exp_f32_e32 v92, v92
	v_exp_f32_e32 v93, v93
	v_pk_add_f32 v[88:89], v[88:89], 1.0 op_sel_hi:[1,0]
	v_pk_add_f32 v[90:91], v[90:91], 1.0 op_sel_hi:[1,0]
	v_pk_add_f32 v[84:85], v[84:85], 1.0 op_sel_hi:[1,0]
	v_pk_add_f32 v[92:93], v[92:93], 1.0 op_sel_hi:[1,0]
	v_rcp_f32_e32 v74, v90
	v_rcp_f32_e32 v75, v91
	v_rcp_f32_e32 v76, v88
	v_rcp_f32_e32 v77, v89
	v_rcp_f32_e32 v78, v84
	v_rcp_f32_e32 v79, v85
	v_rcp_f32_e32 v80, v92
	v_rcp_f32_e32 v81, v93
	v_pk_mul_f32 v[74:75], v[86:87], v[74:75] op_sel_hi:[0,1]
	v_pk_mul_f32 v[76:77], v[86:87], v[76:77] op_sel_hi:[0,1]
	v_add_f32_e32 v138, v138, v139
	v_pk_mul_f32 v[72:73], v[72:73], v[76:77]
	v_pk_mul_f32 v[70:71], v[70:71], v[74:75]
	v_pk_mul_f32 v[74:75], v[86:87], v[78:79] op_sel_hi:[0,1]
	v_pk_mul_f32 v[76:77], v[86:87], v[80:81] op_sel_hi:[0,1]
	ds_bpermute_b32 v139, v163, v138
	v_mad_i64_i32 v[82:83], s[22:23], v162, s57, v[130:131]
	v_pk_mul_f32 v[76:77], v[68:69], v[76:77]
	v_pk_mul_f32 v[68:69], v[66:67], v[74:75]
	v_lshl_add_u64 v[82:83], v[82:83], 0, v[132:133]
	v_cvt_pk_bf16_f32 v66, v70, v71
	v_cvt_pk_bf16_f32 v67, v72, v73
	v_cvt_pk_bf16_f32 v68, v68, v69
	v_cvt_pk_bf16_f32 v69, v76, v77
	global_store_dwordx4 v[82:83], v[66:69], off
	s_waitcnt lgkmcnt(0)
	v_add_f32_e32 v138, v138, v139
	ds_bpermute_b32 v139, v165, v138
	v_mul_f32_e32 v68, 0xbfb8aa3b, v155
	v_pk_mul_f32 v[72:73], v[64:65], v[68:69] op_sel_hi:[1,0]
	v_pk_mul_f32 v[74:75], v[62:63], v[68:69] op_sel_hi:[1,0]
	v_pk_mul_f32 v[76:77], v[60:61], v[68:69] op_sel_hi:[1,0]
	v_pk_mul_f32 v[68:69], v[58:59], v[68:69] op_sel_hi:[1,0]
	v_exp_f32_e32 v74, v74
	v_exp_f32_e32 v75, v75
	v_exp_f32_e32 v72, v72
	v_exp_f32_e32 v73, v73
	v_exp_f32_e32 v68, v68
	v_exp_f32_e32 v69, v69
	v_exp_f32_e32 v76, v76
	v_exp_f32_e32 v77, v77
	v_pk_add_f32 v[72:73], v[72:73], 1.0 op_sel_hi:[1,0]
	v_pk_add_f32 v[74:75], v[74:75], 1.0 op_sel_hi:[1,0]
	v_pk_add_f32 v[68:69], v[68:69], 1.0 op_sel_hi:[1,0]
	v_pk_add_f32 v[76:77], v[76:77], 1.0 op_sel_hi:[1,0]
	v_rcp_f32_e32 v58, v74
	v_rcp_f32_e32 v59, v75
	v_rcp_f32_e32 v60, v72
	v_rcp_f32_e32 v61, v73
	v_rcp_f32_e32 v62, v68
	v_rcp_f32_e32 v63, v69
	v_rcp_f32_e32 v64, v76
	v_rcp_f32_e32 v65, v77
	s_waitcnt lgkmcnt(0)
	v_add_f32_e32 v138, v138, v139
	v_fmamk_f32 v138, v138, 0x3a800000, v223
	v_mul_f32_e32 v70, v155, v155
	v_rsq_f32_e32 v138, v138
	v_pk_mul_f32 v[58:59], v[70:71], v[58:59] op_sel_hi:[0,1]
	v_pk_mul_f32 v[60:61], v[70:71], v[60:61] op_sel_hi:[0,1]
	v_pk_mul_f32 v[56:57], v[56:57], v[60:61]
	v_pk_mul_f32 v[54:55], v[54:55], v[58:59]
	v_pk_mul_f32 v[58:59], v[70:71], v[62:63] op_sel_hi:[0,1]
	v_pk_mul_f32 v[60:61], v[70:71], v[64:65] op_sel_hi:[0,1]
	v_mad_i64_i32 v[66:67], s[22:23], v160, s57, v[130:131]
	v_pk_mul_f32 v[60:61], v[52:53], v[60:61]
	v_pk_mul_f32 v[52:53], v[50:51], v[58:59]
	v_lshl_add_u64 v[66:67], v[66:67], 0, v[132:133]
	v_cvt_pk_bf16_f32 v50, v54, v55
	v_cvt_pk_bf16_f32 v51, v56, v57
	v_cvt_pk_bf16_f32 v52, v52, v53
	v_cvt_pk_bf16_f32 v53, v60, v61
	global_store_dwordx4 v[66:67], v[50:53], off
	v_mul_f32_e32 v54, v138, v138
	s_nop 0
	v_mul_f32_e32 v52, 0xbfb8aa3b, v138
	v_pk_mul_f32 v[56:57], v[48:49], v[52:53] op_sel_hi:[1,0]
	v_pk_mul_f32 v[58:59], v[46:47], v[52:53] op_sel_hi:[1,0]
	v_pk_mul_f32 v[60:61], v[44:45], v[52:53] op_sel_hi:[1,0]
	v_pk_mul_f32 v[52:53], v[42:43], v[52:53] op_sel_hi:[1,0]
	v_exp_f32_e32 v58, v58
	v_exp_f32_e32 v59, v59
	v_exp_f32_e32 v56, v56
	v_exp_f32_e32 v57, v57
	v_exp_f32_e32 v52, v52
	v_exp_f32_e32 v53, v53
	v_exp_f32_e32 v60, v60
	v_exp_f32_e32 v61, v61
	v_pk_add_f32 v[56:57], v[56:57], 1.0 op_sel_hi:[1,0]
	v_pk_add_f32 v[58:59], v[58:59], 1.0 op_sel_hi:[1,0]
	v_pk_add_f32 v[52:53], v[52:53], 1.0 op_sel_hi:[1,0]
	v_pk_add_f32 v[60:61], v[60:61], 1.0 op_sel_hi:[1,0]
	v_rcp_f32_e32 v42, v58
	v_rcp_f32_e32 v43, v59
	v_rcp_f32_e32 v44, v56
	v_rcp_f32_e32 v45, v57
	v_rcp_f32_e32 v46, v52
	v_rcp_f32_e32 v47, v53
	v_rcp_f32_e32 v48, v60
	v_rcp_f32_e32 v49, v61
	v_pk_mul_f32 v[42:43], v[54:55], v[42:43] op_sel_hi:[0,1]
	v_pk_mul_f32 v[44:45], v[54:55], v[44:45] op_sel_hi:[0,1]
	v_pk_mul_f32 v[40:41], v[40:41], v[44:45]
	v_pk_mul_f32 v[38:39], v[38:39], v[42:43]
	v_pk_mul_f32 v[42:43], v[54:55], v[46:47] op_sel_hi:[0,1]
	v_pk_mul_f32 v[44:45], v[54:55], v[48:49] op_sel_hi:[0,1]
	v_mad_i64_i32 v[50:51], s[22:23], v158, s57, v[130:131]
	v_pk_mul_f32 v[44:45], v[36:37], v[44:45]
	v_pk_mul_f32 v[36:37], v[34:35], v[42:43]
	v_lshl_add_u64 v[50:51], v[50:51], 0, v[132:133]
	v_cvt_pk_bf16_f32 v34, v38, v39
	v_cvt_pk_bf16_f32 v35, v40, v41
	v_cvt_pk_bf16_f32 v36, v36, v37
	v_cvt_pk_bf16_f32 v37, v44, v45
	global_store_dwordx4 v[50:51], v[34:37], off
	v_mul_f32_e32 v38, v135, v135
	s_nop 0
	v_mul_f32_e32 v36, 0xbfb8aa3b, v135
	v_pk_mul_f32 v[40:41], v[32:33], v[36:37] op_sel_hi:[1,0]
	v_pk_mul_f32 v[42:43], v[30:31], v[36:37] op_sel_hi:[1,0]
	v_pk_mul_f32 v[44:45], v[28:29], v[36:37] op_sel_hi:[1,0]
	v_pk_mul_f32 v[36:37], v[26:27], v[36:37] op_sel_hi:[1,0]
	v_exp_f32_e32 v42, v42
	v_exp_f32_e32 v43, v43
	v_exp_f32_e32 v40, v40
	v_exp_f32_e32 v41, v41
	v_exp_f32_e32 v36, v36
	v_exp_f32_e32 v37, v37
	v_exp_f32_e32 v44, v44
	v_exp_f32_e32 v45, v45
	v_pk_add_f32 v[40:41], v[40:41], 1.0 op_sel_hi:[1,0]
	v_pk_add_f32 v[42:43], v[42:43], 1.0 op_sel_hi:[1,0]
	v_pk_add_f32 v[36:37], v[36:37], 1.0 op_sel_hi:[1,0]
	v_pk_add_f32 v[44:45], v[44:45], 1.0 op_sel_hi:[1,0]
	v_rcp_f32_e32 v26, v42
	v_rcp_f32_e32 v27, v43
	v_rcp_f32_e32 v28, v40
	v_rcp_f32_e32 v29, v41
	v_rcp_f32_e32 v30, v36
	v_rcp_f32_e32 v31, v37
	v_rcp_f32_e32 v32, v44
	v_rcp_f32_e32 v33, v45
	v_pk_mul_f32 v[26:27], v[38:39], v[26:27] op_sel_hi:[0,1]
	v_pk_mul_f32 v[28:29], v[38:39], v[28:29] op_sel_hi:[0,1]
	v_pk_mul_f32 v[24:25], v[24:25], v[28:29]
	v_pk_mul_f32 v[22:23], v[22:23], v[26:27]
	v_pk_mul_f32 v[26:27], v[38:39], v[30:31] op_sel_hi:[0,1]
	v_pk_mul_f32 v[28:29], v[38:39], v[32:33] op_sel_hi:[0,1]
	v_mad_i64_i32 v[34:35], s[22:23], v156, s57, v[130:131]
	v_pk_mul_f32 v[28:29], v[20:21], v[28:29]
	v_pk_mul_f32 v[20:21], v[18:19], v[26:27]
	v_lshl_add_u64 v[34:35], v[34:35], 0, v[132:133]
	v_cvt_pk_bf16_f32 v18, v22, v23
	v_cvt_pk_bf16_f32 v19, v24, v25
	v_cvt_pk_bf16_f32 v20, v20, v21
	v_cvt_pk_bf16_f32 v21, v28, v29
	global_store_dwordx4 v[34:35], v[18:21], off
	v_mul_f32_e32 v22, v134, v134
	s_nop 0
	v_mul_f32_e32 v20, 0xbfb8aa3b, v134
	v_pk_mul_f32 v[24:25], v[16:17], v[20:21] op_sel_hi:[1,0]
	v_pk_mul_f32 v[26:27], v[14:15], v[20:21] op_sel_hi:[1,0]
	v_pk_mul_f32 v[28:29], v[12:13], v[20:21] op_sel_hi:[1,0]
	v_pk_mul_f32 v[20:21], v[10:11], v[20:21] op_sel_hi:[1,0]
	v_exp_f32_e32 v26, v26
	v_exp_f32_e32 v27, v27
	v_exp_f32_e32 v24, v24
	v_exp_f32_e32 v25, v25
	v_exp_f32_e32 v20, v20
	v_exp_f32_e32 v21, v21
	v_exp_f32_e32 v28, v28
	v_exp_f32_e32 v29, v29
	v_pk_add_f32 v[24:25], v[24:25], 1.0 op_sel_hi:[1,0]
	v_pk_add_f32 v[26:27], v[26:27], 1.0 op_sel_hi:[1,0]
	v_pk_add_f32 v[20:21], v[20:21], 1.0 op_sel_hi:[1,0]
	v_pk_add_f32 v[28:29], v[28:29], 1.0 op_sel_hi:[1,0]
	v_rcp_f32_e32 v10, v26
	v_rcp_f32_e32 v11, v27
	v_rcp_f32_e32 v12, v24
	v_rcp_f32_e32 v13, v25
	v_rcp_f32_e32 v14, v20
	v_rcp_f32_e32 v15, v21
	v_rcp_f32_e32 v16, v28
	v_rcp_f32_e32 v17, v29
	v_pk_mul_f32 v[10:11], v[22:23], v[10:11] op_sel_hi:[0,1]
	v_pk_mul_f32 v[12:13], v[22:23], v[12:13] op_sel_hi:[0,1]
	v_pk_mul_f32 v[8:9], v[8:9], v[12:13]
	v_pk_mul_f32 v[6:7], v[6:7], v[10:11]
	v_pk_mul_f32 v[10:11], v[22:23], v[14:15] op_sel_hi:[0,1]
	v_pk_mul_f32 v[12:13], v[22:23], v[16:17] op_sel_hi:[0,1]
	v_mad_i64_i32 v[18:19], s[22:23], v154, s57, v[130:131]
	v_pk_mul_f32 v[12:13], v[4:5], v[12:13]
	v_pk_mul_f32 v[4:5], v[2:3], v[10:11]
	v_lshl_add_u64 v[18:19], v[18:19], 0, v[132:133]
	v_cvt_pk_bf16_f32 v2, v6, v7
	v_cvt_pk_bf16_f32 v3, v8, v9
	v_cvt_pk_bf16_f32 v4, v4, v5
	v_cvt_pk_bf16_f32 v5, v12, v13
	s_mov_b64 s[22:23], -1
	global_store_dwordx4 v[18:19], v[2:5], off
	s_cbranch_vccnz .LBB0_286
	s_andn2_b64 vcc, exec, s[8:9]
	s_cbranch_vccnz .LBB0_285
	s_barrier
	s_branch .LBB0_285
